# P0 x/ctx->H copy: 34 serialized load-wait-store iterations replaced by one 34-deep straight-line batch with scalar addressing
# baseline (speedup 1.0000x reference)
; __global__ void __launch_bounds__(512) mk_fwd(Params P) {
;     ...
;             const f32x4* x4 = (const f32x4*)P.in[0]; const f32x4* c4 = (const f32x4*)P.in[2]; f32x4* h4 = (f32x4*)H;
;             for (size_t i = (size_t)bid * 512 + tid; i < (size_t)M * 256; i += (size_t)G * 512) {
;                 const int row = (int)(i >> 8), c = (int)(i & 255), bi = row / TB, rr = row - bi * TB;
;                 h4[i] = __builtin_nontemporal_load(rr < CTXL ? &c4[((size_t)bi * CTXL + rr) * 256 + c] : &x4[((size_t)bi * SEQ + (rr - CTXL)) * 256 + c]);
;             }
.LBB0_562:
	s_waitcnt vmcnt(0)
	v_ashrrev_i32_e32 v147, 31, v146
	s_waitcnt lgkmcnt(0)
	v_readlane_b32 s88, v254, 17
	v_readlane_b32 s89, v254, 18
	v_readlane_b32 s92, v254, 21
	v_readlane_b32 s93, v254, 22
	v_lshlrev_b32_e32 v0, 4, v146
	s_mov_b32 s90, s2
	s_mul_i32 s91, s80, 33
.Lcp_batch_test:
	s_add_u32 s3, s90, s91
	s_cmp_lt_u32 s3, 0x2200
	s_cbranch_scc0 .Lcp_tail
	s_mov_b32 s94, s90
	s_cmp_ge_u32 s94, 0x880
	s_cselect_b32 s6, 1, 0
	s_cmp_ge_u32 s94, 0x1100
	s_addc_u32 s6, s6, 0
	s_cmp_ge_u32 s94, 0x1980
	s_addc_u32 s6, s6, 0
	s_mul_i32 s7, s6, 0x880
	s_sub_u32 s7, s94, s7
	s_lshl_b32 s8, s7, 13
	s_cmp_lt_u32 s7, 0x80
	s_cselect_b32 s9, 20, 24
	s_cselect_b64 s[10:11], s[92:93], s[88:89]
	s_cselect_b32 s7, 0, 0x100000
	s_lshl_b32 s6, s6, s9
	s_add_u32 s6, s6, s8
	s_sub_u32 s6, s6, s7
	s_add_u32 s10, s10, s6
	s_addc_u32 s11, s11, 0
	global_load_dwordx4 v[4:7], v0, s[10:11] nt
	s_add_u32 s94, s94, s80
	s_cmp_ge_u32 s94, 0x880
	s_cselect_b32 s6, 1, 0
	s_cmp_ge_u32 s94, 0x1100
	s_addc_u32 s6, s6, 0
	s_cmp_ge_u32 s94, 0x1980
	s_addc_u32 s6, s6, 0
	s_mul_i32 s7, s6, 0x880
	s_sub_u32 s7, s94, s7
	s_lshl_b32 s8, s7, 13
	s_cmp_lt_u32 s7, 0x80
	s_cselect_b32 s9, 20, 24
	s_cselect_b64 s[10:11], s[92:93], s[88:89]
	s_cselect_b32 s7, 0, 0x100000
	s_lshl_b32 s6, s6, s9
	s_add_u32 s6, s6, s8
	s_sub_u32 s6, s6, s7
	s_add_u32 s10, s10, s6
	s_addc_u32 s11, s11, 0
	global_load_dwordx4 v[8:11], v0, s[10:11] nt
	s_add_u32 s94, s94, s80
	s_cmp_ge_u32 s94, 0x880
	s_cselect_b32 s6, 1, 0
	s_cmp_ge_u32 s94, 0x1100
	s_addc_u32 s6, s6, 0
	s_cmp_ge_u32 s94, 0x1980
	s_addc_u32 s6, s6, 0
	s_mul_i32 s7, s6, 0x880
	s_sub_u32 s7, s94, s7
	s_lshl_b32 s8, s7, 13
	s_cmp_lt_u32 s7, 0x80
	s_cselect_b32 s9, 20, 24
	s_cselect_b64 s[10:11], s[92:93], s[88:89]
	s_cselect_b32 s7, 0, 0x100000
	s_lshl_b32 s6, s6, s9
	s_add_u32 s6, s6, s8
	s_sub_u32 s6, s6, s7
	s_add_u32 s10, s10, s6
	s_addc_u32 s11, s11, 0
	global_load_dwordx4 v[12:15], v0, s[10:11] nt
	s_add_u32 s94, s94, s80
	s_cmp_ge_u32 s94, 0x880
	s_cselect_b32 s6, 1, 0
	s_cmp_ge_u32 s94, 0x1100
	s_addc_u32 s6, s6, 0
	s_cmp_ge_u32 s94, 0x1980
	s_addc_u32 s6, s6, 0
	s_mul_i32 s7, s6, 0x880
	s_sub_u32 s7, s94, s7
	s_lshl_b32 s8, s7, 13
	s_cmp_lt_u32 s7, 0x80
	s_cselect_b32 s9, 20, 24
	s_cselect_b64 s[10:11], s[92:93], s[88:89]
	s_cselect_b32 s7, 0, 0x100000
	s_lshl_b32 s6, s6, s9
	s_add_u32 s6, s6, s8
	s_sub_u32 s6, s6, s7
	s_add_u32 s10, s10, s6
	s_addc_u32 s11, s11, 0
	global_load_dwordx4 v[16:19], v0, s[10:11] nt
	s_add_u32 s94, s94, s80
	s_cmp_ge_u32 s94, 0x880
	s_cselect_b32 s6, 1, 0
	s_cmp_ge_u32 s94, 0x1100
	s_addc_u32 s6, s6, 0
	s_cmp_ge_u32 s94, 0x1980
	s_addc_u32 s6, s6, 0
	s_mul_i32 s7, s6, 0x880
	s_sub_u32 s7, s94, s7
	s_lshl_b32 s8, s7, 13
	s_cmp_lt_u32 s7, 0x80
	s_cselect_b32 s9, 20, 24
	s_cselect_b64 s[10:11], s[92:93], s[88:89]
	s_cselect_b32 s7, 0, 0x100000
	s_lshl_b32 s6, s6, s9
	s_add_u32 s6, s6, s8
	s_sub_u32 s6, s6, s7
	s_add_u32 s10, s10, s6
	s_addc_u32 s11, s11, 0
	global_load_dwordx4 v[20:23], v0, s[10:11] nt
	s_add_u32 s94, s94, s80
	s_cmp_ge_u32 s94, 0x880
	s_cselect_b32 s6, 1, 0
	s_cmp_ge_u32 s94, 0x1100
	s_addc_u32 s6, s6, 0
	s_cmp_ge_u32 s94, 0x1980
	s_addc_u32 s6, s6, 0
	s_mul_i32 s7, s6, 0x880
	s_sub_u32 s7, s94, s7
	s_lshl_b32 s8, s7, 13
	s_cmp_lt_u32 s7, 0x80
	s_cselect_b32 s9, 20, 24
	s_cselect_b64 s[10:11], s[92:93], s[88:89]
	s_cselect_b32 s7, 0, 0x100000
	s_lshl_b32 s6, s6, s9
	s_add_u32 s6, s6, s8
	s_sub_u32 s6, s6, s7
	s_add_u32 s10, s10, s6
	s_addc_u32 s11, s11, 0
	global_load_dwordx4 v[24:27], v0, s[10:11] nt
	s_add_u32 s94, s94, s80
	s_cmp_ge_u32 s94, 0x880
	s_cselect_b32 s6, 1, 0
	s_cmp_ge_u32 s94, 0x1100
	s_addc_u32 s6, s6, 0
	s_cmp_ge_u32 s94, 0x1980
	s_addc_u32 s6, s6, 0
	s_mul_i32 s7, s6, 0x880
	s_sub_u32 s7, s94, s7
	s_lshl_b32 s8, s7, 13
	s_cmp_lt_u32 s7, 0x80
	s_cselect_b32 s9, 20, 24
	s_cselect_b64 s[10:11], s[92:93], s[88:89]
	s_cselect_b32 s7, 0, 0x100000
	s_lshl_b32 s6, s6, s9
	s_add_u32 s6, s6, s8
	s_sub_u32 s6, s6, s7
	s_add_u32 s10, s10, s6
	s_addc_u32 s11, s11, 0
	global_load_dwordx4 v[28:31], v0, s[10:11] nt
	s_add_u32 s94, s94, s80
	s_cmp_ge_u32 s94, 0x880
	s_cselect_b32 s6, 1, 0
	s_cmp_ge_u32 s94, 0x1100
	s_addc_u32 s6, s6, 0
	s_cmp_ge_u32 s94, 0x1980
	s_addc_u32 s6, s6, 0
	s_mul_i32 s7, s6, 0x880
	s_sub_u32 s7, s94, s7
	s_lshl_b32 s8, s7, 13
	s_cmp_lt_u32 s7, 0x80
	s_cselect_b32 s9, 20, 24
	s_cselect_b64 s[10:11], s[92:93], s[88:89]
	s_cselect_b32 s7, 0, 0x100000
	s_lshl_b32 s6, s6, s9
	s_add_u32 s6, s6, s8
	s_sub_u32 s6, s6, s7
	s_add_u32 s10, s10, s6
	s_addc_u32 s11, s11, 0
	global_load_dwordx4 v[32:35], v0, s[10:11] nt
	s_add_u32 s94, s94, s80
	s_cmp_ge_u32 s94, 0x880
	s_cselect_b32 s6, 1, 0
	s_cmp_ge_u32 s94, 0x1100
	s_addc_u32 s6, s6, 0
	s_cmp_ge_u32 s94, 0x1980
	s_addc_u32 s6, s6, 0
	s_mul_i32 s7, s6, 0x880
	s_sub_u32 s7, s94, s7
	s_lshl_b32 s8, s7, 13
	s_cmp_lt_u32 s7, 0x80
	s_cselect_b32 s9, 20, 24
	s_cselect_b64 s[10:11], s[92:93], s[88:89]
	s_cselect_b32 s7, 0, 0x100000
	s_lshl_b32 s6, s6, s9
	s_add_u32 s6, s6, s8
	s_sub_u32 s6, s6, s7
	s_add_u32 s10, s10, s6
	s_addc_u32 s11, s11, 0
	global_load_dwordx4 v[36:39], v0, s[10:11] nt
	s_add_u32 s94, s94, s80
	s_cmp_ge_u32 s94, 0x880
	s_cselect_b32 s6, 1, 0
	s_cmp_ge_u32 s94, 0x1100
	s_addc_u32 s6, s6, 0
	s_cmp_ge_u32 s94, 0x1980
	s_addc_u32 s6, s6, 0
	s_mul_i32 s7, s6, 0x880
	s_sub_u32 s7, s94, s7
	s_lshl_b32 s8, s7, 13
	s_cmp_lt_u32 s7, 0x80
	s_cselect_b32 s9, 20, 24
	s_cselect_b64 s[10:11], s[92:93], s[88:89]
	s_cselect_b32 s7, 0, 0x100000
	s_lshl_b32 s6, s6, s9
	s_add_u32 s6, s6, s8
	s_sub_u32 s6, s6, s7
	s_add_u32 s10, s10, s6
	s_addc_u32 s11, s11, 0
	global_load_dwordx4 v[40:43], v0, s[10:11] nt
; __global__ void __launch_bounds__(512) mk_fwd(Params P) {
;     ...
;             const f32x4* x4 = (const f32x4*)P.in[0]; const f32x4* c4 = (const f32x4*)P.in[2]; f32x4* h4 = (f32x4*)H;
;             for (size_t i = (size_t)bid * 512 + tid; i < (size_t)M * 256; i += (size_t)G * 512) {
;                 const int row = (int)(i >> 8), c = (int)(i & 255), bi = row / TB, rr = row - bi * TB;
;                 h4[i] = __builtin_nontemporal_load(rr < CTXL ? &c4[((size_t)bi * CTXL + rr) * 256 + c] : &x4[((size_t)bi * SEQ + (rr - CTXL)) * 256 + c]);
;             }
	s_add_u32 s94, s94, s80
	s_cmp_ge_u32 s94, 0x880
	s_cselect_b32 s6, 1, 0
	s_cmp_ge_u32 s94, 0x1100
	s_addc_u32 s6, s6, 0
	s_cmp_ge_u32 s94, 0x1980
	s_addc_u32 s6, s6, 0
	s_mul_i32 s7, s6, 0x880
	s_sub_u32 s7, s94, s7
	s_lshl_b32 s8, s7, 13
	s_cmp_lt_u32 s7, 0x80
	s_cselect_b32 s9, 20, 24
	s_cselect_b64 s[10:11], s[92:93], s[88:89]
	s_cselect_b32 s7, 0, 0x100000
	s_lshl_b32 s6, s6, s9
	s_add_u32 s6, s6, s8
	s_sub_u32 s6, s6, s7
	s_add_u32 s10, s10, s6
	s_addc_u32 s11, s11, 0
	global_load_dwordx4 v[44:47], v0, s[10:11] nt
	s_add_u32 s94, s94, s80
	s_cmp_ge_u32 s94, 0x880
	s_cselect_b32 s6, 1, 0
	s_cmp_ge_u32 s94, 0x1100
	s_addc_u32 s6, s6, 0
	s_cmp_ge_u32 s94, 0x1980
	s_addc_u32 s6, s6, 0
	s_mul_i32 s7, s6, 0x880
	s_sub_u32 s7, s94, s7
	s_lshl_b32 s8, s7, 13
	s_cmp_lt_u32 s7, 0x80
	s_cselect_b32 s9, 20, 24
	s_cselect_b64 s[10:11], s[92:93], s[88:89]
	s_cselect_b32 s7, 0, 0x100000
	s_lshl_b32 s6, s6, s9
	s_add_u32 s6, s6, s8
	s_sub_u32 s6, s6, s7
	s_add_u32 s10, s10, s6
	s_addc_u32 s11, s11, 0
	global_load_dwordx4 v[48:51], v0, s[10:11] nt
	s_add_u32 s94, s94, s80
	s_cmp_ge_u32 s94, 0x880
	s_cselect_b32 s6, 1, 0
	s_cmp_ge_u32 s94, 0x1100
	s_addc_u32 s6, s6, 0
	s_cmp_ge_u32 s94, 0x1980
	s_addc_u32 s6, s6, 0
	s_mul_i32 s7, s6, 0x880
	s_sub_u32 s7, s94, s7
	s_lshl_b32 s8, s7, 13
	s_cmp_lt_u32 s7, 0x80
	s_cselect_b32 s9, 20, 24
	s_cselect_b64 s[10:11], s[92:93], s[88:89]
	s_cselect_b32 s7, 0, 0x100000
	s_lshl_b32 s6, s6, s9
	s_add_u32 s6, s6, s8
	s_sub_u32 s6, s6, s7
	s_add_u32 s10, s10, s6
	s_addc_u32 s11, s11, 0
	global_load_dwordx4 v[52:55], v0, s[10:11] nt
	s_add_u32 s94, s94, s80
	s_cmp_ge_u32 s94, 0x880
	s_cselect_b32 s6, 1, 0
	s_cmp_ge_u32 s94, 0x1100
	s_addc_u32 s6, s6, 0
	s_cmp_ge_u32 s94, 0x1980
	s_addc_u32 s6, s6, 0
	s_mul_i32 s7, s6, 0x880
	s_sub_u32 s7, s94, s7
	s_lshl_b32 s8, s7, 13
	s_cmp_lt_u32 s7, 0x80
	s_cselect_b32 s9, 20, 24
	s_cselect_b64 s[10:11], s[92:93], s[88:89]
	s_cselect_b32 s7, 0, 0x100000
	s_lshl_b32 s6, s6, s9
	s_add_u32 s6, s6, s8
	s_sub_u32 s6, s6, s7
	s_add_u32 s10, s10, s6
	s_addc_u32 s11, s11, 0
	global_load_dwordx4 v[56:59], v0, s[10:11] nt
	s_add_u32 s94, s94, s80
	s_cmp_ge_u32 s94, 0x880
	s_cselect_b32 s6, 1, 0
	s_cmp_ge_u32 s94, 0x1100
	s_addc_u32 s6, s6, 0
	s_cmp_ge_u32 s94, 0x1980
	s_addc_u32 s6, s6, 0
	s_mul_i32 s7, s6, 0x880
	s_sub_u32 s7, s94, s7
	s_lshl_b32 s8, s7, 13
	s_cmp_lt_u32 s7, 0x80
	s_cselect_b32 s9, 20, 24
	s_cselect_b64 s[10:11], s[92:93], s[88:89]
	s_cselect_b32 s7, 0, 0x100000
	s_lshl_b32 s6, s6, s9
	s_add_u32 s6, s6, s8
	s_sub_u32 s6, s6, s7
	s_add_u32 s10, s10, s6
	s_addc_u32 s11, s11, 0
	global_load_dwordx4 v[60:63], v0, s[10:11] nt
	s_add_u32 s94, s94, s80
	s_cmp_ge_u32 s94, 0x880
	s_cselect_b32 s6, 1, 0
	s_cmp_ge_u32 s94, 0x1100
	s_addc_u32 s6, s6, 0
	s_cmp_ge_u32 s94, 0x1980
	s_addc_u32 s6, s6, 0
	s_mul_i32 s7, s6, 0x880
	s_sub_u32 s7, s94, s7
	s_lshl_b32 s8, s7, 13
	s_cmp_lt_u32 s7, 0x80
	s_cselect_b32 s9, 20, 24
	s_cselect_b64 s[10:11], s[92:93], s[88:89]
	s_cselect_b32 s7, 0, 0x100000
	s_lshl_b32 s6, s6, s9
	s_add_u32 s6, s6, s8
	s_sub_u32 s6, s6, s7
	s_add_u32 s10, s10, s6
	s_addc_u32 s11, s11, 0
	global_load_dwordx4 v[64:67], v0, s[10:11] nt
	s_add_u32 s94, s94, s80
	s_cmp_ge_u32 s94, 0x880
	s_cselect_b32 s6, 1, 0
	s_cmp_ge_u32 s94, 0x1100
	s_addc_u32 s6, s6, 0
	s_cmp_ge_u32 s94, 0x1980
	s_addc_u32 s6, s6, 0
	s_mul_i32 s7, s6, 0x880
	s_sub_u32 s7, s94, s7
	s_lshl_b32 s8, s7, 13
	s_cmp_lt_u32 s7, 0x80
	s_cselect_b32 s9, 20, 24
	s_cselect_b64 s[10:11], s[92:93], s[88:89]
	s_cselect_b32 s7, 0, 0x100000
	s_lshl_b32 s6, s6, s9
	s_add_u32 s6, s6, s8
	s_sub_u32 s6, s6, s7
	s_add_u32 s10, s10, s6
	s_addc_u32 s11, s11, 0
	global_load_dwordx4 v[68:71], v0, s[10:11] nt
	s_add_u32 s94, s94, s80
	s_cmp_ge_u32 s94, 0x880
	s_cselect_b32 s6, 1, 0
	s_cmp_ge_u32 s94, 0x1100
	s_addc_u32 s6, s6, 0
	s_cmp_ge_u32 s94, 0x1980
	s_addc_u32 s6, s6, 0
	s_mul_i32 s7, s6, 0x880
	s_sub_u32 s7, s94, s7
	s_lshl_b32 s8, s7, 13
	s_cmp_lt_u32 s7, 0x80
	s_cselect_b32 s9, 20, 24
	s_cselect_b64 s[10:11], s[92:93], s[88:89]
	s_cselect_b32 s7, 0, 0x100000
	s_lshl_b32 s6, s6, s9
	s_add_u32 s6, s6, s8
	s_sub_u32 s6, s6, s7
	s_add_u32 s10, s10, s6
	s_addc_u32 s11, s11, 0
	global_load_dwordx4 v[72:75], v0, s[10:11] nt
	s_add_u32 s94, s94, s80
	s_cmp_ge_u32 s94, 0x880
	s_cselect_b32 s6, 1, 0
	s_cmp_ge_u32 s94, 0x1100
	s_addc_u32 s6, s6, 0
	s_cmp_ge_u32 s94, 0x1980
	s_addc_u32 s6, s6, 0
	s_mul_i32 s7, s6, 0x880
	s_sub_u32 s7, s94, s7
	s_lshl_b32 s8, s7, 13
	s_cmp_lt_u32 s7, 0x80
	s_cselect_b32 s9, 20, 24
	s_cselect_b64 s[10:11], s[92:93], s[88:89]
	s_cselect_b32 s7, 0, 0x100000
	s_lshl_b32 s6, s6, s9
	s_add_u32 s6, s6, s8
	s_sub_u32 s6, s6, s7
	s_add_u32 s10, s10, s6
	s_addc_u32 s11, s11, 0
	global_load_dwordx4 v[76:79], v0, s[10:11] nt
	s_add_u32 s94, s94, s80
	s_cmp_ge_u32 s94, 0x880
	s_cselect_b32 s6, 1, 0
	s_cmp_ge_u32 s94, 0x1100
	s_addc_u32 s6, s6, 0
	s_cmp_ge_u32 s94, 0x1980
	s_addc_u32 s6, s6, 0
	s_mul_i32 s7, s6, 0x880
	s_sub_u32 s7, s94, s7
	s_lshl_b32 s8, s7, 13
	s_cmp_lt_u32 s7, 0x80
	s_cselect_b32 s9, 20, 24
	s_cselect_b64 s[10:11], s[92:93], s[88:89]
	s_cselect_b32 s7, 0, 0x100000
	s_lshl_b32 s6, s6, s9
	s_add_u32 s6, s6, s8
	s_sub_u32 s6, s6, s7
	s_add_u32 s10, s10, s6
	s_addc_u32 s11, s11, 0
	global_load_dwordx4 v[80:83], v0, s[10:11] nt
	s_add_u32 s94, s94, s80
	s_cmp_ge_u32 s94, 0x880
	s_cselect_b32 s6, 1, 0
	s_cmp_ge_u32 s94, 0x1100
	s_addc_u32 s6, s6, 0
	s_cmp_ge_u32 s94, 0x1980
	s_addc_u32 s6, s6, 0
	s_mul_i32 s7, s6, 0x880
	s_sub_u32 s7, s94, s7
	s_lshl_b32 s8, s7, 13
	s_cmp_lt_u32 s7, 0x80
	s_cselect_b32 s9, 20, 24
	s_cselect_b64 s[10:11], s[92:93], s[88:89]
	s_cselect_b32 s7, 0, 0x100000
; __global__ void __launch_bounds__(512) mk_fwd(Params P) {
;     ...
;             const f32x4* x4 = (const f32x4*)P.in[0]; const f32x4* c4 = (const f32x4*)P.in[2]; f32x4* h4 = (f32x4*)H;
;             for (size_t i = (size_t)bid * 512 + tid; i < (size_t)M * 256; i += (size_t)G * 512) {
;                 const int row = (int)(i >> 8), c = (int)(i & 255), bi = row / TB, rr = row - bi * TB;
;                 h4[i] = __builtin_nontemporal_load(rr < CTXL ? &c4[((size_t)bi * CTXL + rr) * 256 + c] : &x4[((size_t)bi * SEQ + (rr - CTXL)) * 256 + c]);
;             }
	s_lshl_b32 s6, s6, s9
	s_add_u32 s6, s6, s8
	s_sub_u32 s6, s6, s7
	s_add_u32 s10, s10, s6
	s_addc_u32 s11, s11, 0
	global_load_dwordx4 v[84:87], v0, s[10:11] nt
	s_add_u32 s94, s94, s80
	s_cmp_ge_u32 s94, 0x880
	s_cselect_b32 s6, 1, 0
	s_cmp_ge_u32 s94, 0x1100
	s_addc_u32 s6, s6, 0
	s_cmp_ge_u32 s94, 0x1980
	s_addc_u32 s6, s6, 0
	s_mul_i32 s7, s6, 0x880
	s_sub_u32 s7, s94, s7
	s_lshl_b32 s8, s7, 13
	s_cmp_lt_u32 s7, 0x80
	s_cselect_b32 s9, 20, 24
	s_cselect_b64 s[10:11], s[92:93], s[88:89]
	s_cselect_b32 s7, 0, 0x100000
	s_lshl_b32 s6, s6, s9
	s_add_u32 s6, s6, s8
	s_sub_u32 s6, s6, s7
	s_add_u32 s10, s10, s6
	s_addc_u32 s11, s11, 0
	global_load_dwordx4 v[88:91], v0, s[10:11] nt
	s_add_u32 s94, s94, s80
	s_cmp_ge_u32 s94, 0x880
	s_cselect_b32 s6, 1, 0
	s_cmp_ge_u32 s94, 0x1100
	s_addc_u32 s6, s6, 0
	s_cmp_ge_u32 s94, 0x1980
	s_addc_u32 s6, s6, 0
	s_mul_i32 s7, s6, 0x880
	s_sub_u32 s7, s94, s7
	s_lshl_b32 s8, s7, 13
	s_cmp_lt_u32 s7, 0x80
	s_cselect_b32 s9, 20, 24
	s_cselect_b64 s[10:11], s[92:93], s[88:89]
	s_cselect_b32 s7, 0, 0x100000
	s_lshl_b32 s6, s6, s9
	s_add_u32 s6, s6, s8
	s_sub_u32 s6, s6, s7
	s_add_u32 s10, s10, s6
	s_addc_u32 s11, s11, 0
	global_load_dwordx4 v[92:95], v0, s[10:11] nt
	s_add_u32 s94, s94, s80
	s_cmp_ge_u32 s94, 0x880
	s_cselect_b32 s6, 1, 0
	s_cmp_ge_u32 s94, 0x1100
	s_addc_u32 s6, s6, 0
	s_cmp_ge_u32 s94, 0x1980
	s_addc_u32 s6, s6, 0
	s_mul_i32 s7, s6, 0x880
	s_sub_u32 s7, s94, s7
	s_lshl_b32 s8, s7, 13
	s_cmp_lt_u32 s7, 0x80
	s_cselect_b32 s9, 20, 24
	s_cselect_b64 s[10:11], s[92:93], s[88:89]
	s_cselect_b32 s7, 0, 0x100000
	s_lshl_b32 s6, s6, s9
	s_add_u32 s6, s6, s8
	s_sub_u32 s6, s6, s7
	s_add_u32 s10, s10, s6
	s_addc_u32 s11, s11, 0
	global_load_dwordx4 v[96:99], v0, s[10:11] nt
	s_add_u32 s94, s94, s80
	s_cmp_ge_u32 s94, 0x880
	s_cselect_b32 s6, 1, 0
	s_cmp_ge_u32 s94, 0x1100
	s_addc_u32 s6, s6, 0
	s_cmp_ge_u32 s94, 0x1980
	s_addc_u32 s6, s6, 0
	s_mul_i32 s7, s6, 0x880
	s_sub_u32 s7, s94, s7
	s_lshl_b32 s8, s7, 13
	s_cmp_lt_u32 s7, 0x80
	s_cselect_b32 s9, 20, 24
	s_cselect_b64 s[10:11], s[92:93], s[88:89]
	s_cselect_b32 s7, 0, 0x100000
	s_lshl_b32 s6, s6, s9
	s_add_u32 s6, s6, s8
	s_sub_u32 s6, s6, s7
	s_add_u32 s10, s10, s6
	s_addc_u32 s11, s11, 0
	global_load_dwordx4 v[100:103], v0, s[10:11] nt
	s_add_u32 s94, s94, s80
	s_cmp_ge_u32 s94, 0x880
	s_cselect_b32 s6, 1, 0
	s_cmp_ge_u32 s94, 0x1100
	s_addc_u32 s6, s6, 0
	s_cmp_ge_u32 s94, 0x1980
	s_addc_u32 s6, s6, 0
	s_mul_i32 s7, s6, 0x880
	s_sub_u32 s7, s94, s7
	s_lshl_b32 s8, s7, 13
	s_cmp_lt_u32 s7, 0x80
	s_cselect_b32 s9, 20, 24
	s_cselect_b64 s[10:11], s[92:93], s[88:89]
	s_cselect_b32 s7, 0, 0x100000
	s_lshl_b32 s6, s6, s9
	s_add_u32 s6, s6, s8
	s_sub_u32 s6, s6, s7
	s_add_u32 s10, s10, s6
	s_addc_u32 s11, s11, 0
	global_load_dwordx4 v[104:107], v0, s[10:11] nt
	s_add_u32 s94, s94, s80
	s_cmp_ge_u32 s94, 0x880
	s_cselect_b32 s6, 1, 0
	s_cmp_ge_u32 s94, 0x1100
	s_addc_u32 s6, s6, 0
	s_cmp_ge_u32 s94, 0x1980
	s_addc_u32 s6, s6, 0
	s_mul_i32 s7, s6, 0x880
	s_sub_u32 s7, s94, s7
	s_lshl_b32 s8, s7, 13
	s_cmp_lt_u32 s7, 0x80
	s_cselect_b32 s9, 20, 24
	s_cselect_b64 s[10:11], s[92:93], s[88:89]
	s_cselect_b32 s7, 0, 0x100000
	s_lshl_b32 s6, s6, s9
	s_add_u32 s6, s6, s8
	s_sub_u32 s6, s6, s7
	s_add_u32 s10, s10, s6
	s_addc_u32 s11, s11, 0
	global_load_dwordx4 v[108:111], v0, s[10:11] nt
	s_add_u32 s94, s94, s80
	s_cmp_ge_u32 s94, 0x880
	s_cselect_b32 s6, 1, 0
	s_cmp_ge_u32 s94, 0x1100
	s_addc_u32 s6, s6, 0
	s_cmp_ge_u32 s94, 0x1980
	s_addc_u32 s6, s6, 0
	s_mul_i32 s7, s6, 0x880
	s_sub_u32 s7, s94, s7
	s_lshl_b32 s8, s7, 13
	s_cmp_lt_u32 s7, 0x80
	s_cselect_b32 s9, 20, 24
	s_cselect_b64 s[10:11], s[92:93], s[88:89]
	s_cselect_b32 s7, 0, 0x100000
	s_lshl_b32 s6, s6, s9
	s_add_u32 s6, s6, s8
	s_sub_u32 s6, s6, s7
	s_add_u32 s10, s10, s6
	s_addc_u32 s11, s11, 0
	global_load_dwordx4 v[112:115], v0, s[10:11] nt
	s_add_u32 s94, s94, s80
	s_cmp_ge_u32 s94, 0x880
	s_cselect_b32 s6, 1, 0
	s_cmp_ge_u32 s94, 0x1100
	s_addc_u32 s6, s6, 0
	s_cmp_ge_u32 s94, 0x1980
	s_addc_u32 s6, s6, 0
	s_mul_i32 s7, s6, 0x880
	s_sub_u32 s7, s94, s7
	s_lshl_b32 s8, s7, 13
	s_cmp_lt_u32 s7, 0x80
	s_cselect_b32 s9, 20, 24
	s_cselect_b64 s[10:11], s[92:93], s[88:89]
	s_cselect_b32 s7, 0, 0x100000
	s_lshl_b32 s6, s6, s9
	s_add_u32 s6, s6, s8
	s_sub_u32 s6, s6, s7
	s_add_u32 s10, s10, s6
	s_addc_u32 s11, s11, 0
	global_load_dwordx4 v[116:119], v0, s[10:11] nt
	s_add_u32 s94, s94, s80
	s_cmp_ge_u32 s94, 0x880
	s_cselect_b32 s6, 1, 0
	s_cmp_ge_u32 s94, 0x1100
	s_addc_u32 s6, s6, 0
	s_cmp_ge_u32 s94, 0x1980
	s_addc_u32 s6, s6, 0
	s_mul_i32 s7, s6, 0x880
	s_sub_u32 s7, s94, s7
	s_lshl_b32 s8, s7, 13
	s_cmp_lt_u32 s7, 0x80
	s_cselect_b32 s9, 20, 24
	s_cselect_b64 s[10:11], s[92:93], s[88:89]
	s_cselect_b32 s7, 0, 0x100000
	s_lshl_b32 s6, s6, s9
	s_add_u32 s6, s6, s8
	s_sub_u32 s6, s6, s7
	s_add_u32 s10, s10, s6
	s_addc_u32 s11, s11, 0
	global_load_dwordx4 v[120:123], v0, s[10:11] nt
	s_add_u32 s94, s94, s80
	s_cmp_ge_u32 s94, 0x880
	s_cselect_b32 s6, 1, 0
	s_cmp_ge_u32 s94, 0x1100
	s_addc_u32 s6, s6, 0
	s_cmp_ge_u32 s94, 0x1980
	s_addc_u32 s6, s6, 0
	s_mul_i32 s7, s6, 0x880
	s_sub_u32 s7, s94, s7
	s_lshl_b32 s8, s7, 13
	s_cmp_lt_u32 s7, 0x80
	s_cselect_b32 s9, 20, 24
	s_cselect_b64 s[10:11], s[92:93], s[88:89]
	s_cselect_b32 s7, 0, 0x100000
	s_lshl_b32 s6, s6, s9
	s_add_u32 s6, s6, s8
	s_sub_u32 s6, s6, s7
	s_add_u32 s10, s10, s6
	s_addc_u32 s11, s11, 0
	global_load_dwordx4 v[124:127], v0, s[10:11] nt
	s_add_u32 s94, s94, s80
	s_cmp_ge_u32 s94, 0x880
	s_cselect_b32 s6, 1, 0
	s_cmp_ge_u32 s94, 0x1100
	s_addc_u32 s6, s6, 0
	s_cmp_ge_u32 s94, 0x1980
	s_addc_u32 s6, s6, 0
	s_mul_i32 s7, s6, 0x880
; __global__ void __launch_bounds__(512) mk_fwd(Params P) {
;     ...
;             for (size_t i = (size_t)bid * 512 + tid; i < (size_t)M * 256; i += (size_t)G * 512) {
;                 const int row = (int)(i >> 8), c = (int)(i & 255), bi = row / TB, rr = row - bi * TB;
;                 h4[i] = __builtin_nontemporal_load(rr < CTXL ? &c4[((size_t)bi * CTXL + rr) * 256 + c] : &x4[((size_t)bi * SEQ + (rr - CTXL)) * 256 + c]);
;             }
	s_sub_u32 s7, s94, s7
	s_lshl_b32 s8, s7, 13
	s_cmp_lt_u32 s7, 0x80
	s_cselect_b32 s9, 20, 24
	s_cselect_b64 s[10:11], s[92:93], s[88:89]
	s_cselect_b32 s7, 0, 0x100000
	s_lshl_b32 s6, s6, s9
	s_add_u32 s6, s6, s8
	s_sub_u32 s6, s6, s7
	s_add_u32 s10, s10, s6
	s_addc_u32 s11, s11, 0
	global_load_dwordx4 v[128:131], v0, s[10:11] nt
	s_add_u32 s94, s94, s80
	s_cmp_ge_u32 s94, 0x880
	s_cselect_b32 s6, 1, 0
	s_cmp_ge_u32 s94, 0x1100
	s_addc_u32 s6, s6, 0
	s_cmp_ge_u32 s94, 0x1980
	s_addc_u32 s6, s6, 0
	s_mul_i32 s7, s6, 0x880
	s_sub_u32 s7, s94, s7
	s_lshl_b32 s8, s7, 13
	s_cmp_lt_u32 s7, 0x80
	s_cselect_b32 s9, 20, 24
	s_cselect_b64 s[10:11], s[92:93], s[88:89]
	s_cselect_b32 s7, 0, 0x100000
	s_lshl_b32 s6, s6, s9
	s_add_u32 s6, s6, s8
	s_sub_u32 s6, s6, s7
	s_add_u32 s10, s10, s6
	s_addc_u32 s11, s11, 0
	global_load_dwordx4 v[132:135], v0, s[10:11] nt
	s_add_u32 s94, s94, s80
	s_cmp_ge_u32 s94, 0x880
	s_cselect_b32 s6, 1, 0
	s_cmp_ge_u32 s94, 0x1100
	s_addc_u32 s6, s6, 0
	s_cmp_ge_u32 s94, 0x1980
	s_addc_u32 s6, s6, 0
	s_mul_i32 s7, s6, 0x880
	s_sub_u32 s7, s94, s7
	s_lshl_b32 s8, s7, 13
	s_cmp_lt_u32 s7, 0x80
	s_cselect_b32 s9, 20, 24
	s_cselect_b64 s[10:11], s[92:93], s[88:89]
	s_cselect_b32 s7, 0, 0x100000
	s_lshl_b32 s6, s6, s9
	s_add_u32 s6, s6, s8
	s_sub_u32 s6, s6, s7
	s_add_u32 s10, s10, s6
	s_addc_u32 s11, s11, 0
	global_load_dwordx4 v[136:139], v0, s[10:11] nt
	s_add_u32 s94, s94, s80
	s_mov_b32 s94, s90
	s_lshl_b32 s6, s94, 13
	s_add_u32 s10, s0, s6
	s_addc_u32 s11, s1, 0
	s_waitcnt vmcnt(33)
	global_store_dwordx4 v0, v[4:7], s[10:11]
	s_add_u32 s94, s94, s80
	s_lshl_b32 s6, s94, 13
	s_add_u32 s10, s0, s6
	s_addc_u32 s11, s1, 0
	s_waitcnt vmcnt(33)
	global_store_dwordx4 v0, v[8:11], s[10:11]
	s_add_u32 s94, s94, s80
	s_lshl_b32 s6, s94, 13
	s_add_u32 s10, s0, s6
	s_addc_u32 s11, s1, 0
	s_waitcnt vmcnt(33)
	global_store_dwordx4 v0, v[12:15], s[10:11]
	s_add_u32 s94, s94, s80
	s_lshl_b32 s6, s94, 13
	s_add_u32 s10, s0, s6
	s_addc_u32 s11, s1, 0
	s_waitcnt vmcnt(33)
	global_store_dwordx4 v0, v[16:19], s[10:11]
	s_add_u32 s94, s94, s80
	s_lshl_b32 s6, s94, 13
	s_add_u32 s10, s0, s6
	s_addc_u32 s11, s1, 0
	s_waitcnt vmcnt(33)
	global_store_dwordx4 v0, v[20:23], s[10:11]
	s_add_u32 s94, s94, s80
	s_lshl_b32 s6, s94, 13
	s_add_u32 s10, s0, s6
	s_addc_u32 s11, s1, 0
	s_waitcnt vmcnt(33)
	global_store_dwordx4 v0, v[24:27], s[10:11]
	s_add_u32 s94, s94, s80
	s_lshl_b32 s6, s94, 13
	s_add_u32 s10, s0, s6
	s_addc_u32 s11, s1, 0
	s_waitcnt vmcnt(33)
	global_store_dwordx4 v0, v[28:31], s[10:11]
	s_add_u32 s94, s94, s80
	s_lshl_b32 s6, s94, 13
	s_add_u32 s10, s0, s6
	s_addc_u32 s11, s1, 0
	s_waitcnt vmcnt(33)
	global_store_dwordx4 v0, v[32:35], s[10:11]
	s_add_u32 s94, s94, s80
	s_lshl_b32 s6, s94, 13
	s_add_u32 s10, s0, s6
	s_addc_u32 s11, s1, 0
	s_waitcnt vmcnt(33)
	global_store_dwordx4 v0, v[36:39], s[10:11]
	s_add_u32 s94, s94, s80
	s_lshl_b32 s6, s94, 13
	s_add_u32 s10, s0, s6
	s_addc_u32 s11, s1, 0
	s_waitcnt vmcnt(33)
	global_store_dwordx4 v0, v[40:43], s[10:11]
	s_add_u32 s94, s94, s80
	s_lshl_b32 s6, s94, 13
	s_add_u32 s10, s0, s6
	s_addc_u32 s11, s1, 0
	s_waitcnt vmcnt(33)
	global_store_dwordx4 v0, v[44:47], s[10:11]
	s_add_u32 s94, s94, s80
	s_lshl_b32 s6, s94, 13
	s_add_u32 s10, s0, s6
	s_addc_u32 s11, s1, 0
	s_waitcnt vmcnt(33)
	global_store_dwordx4 v0, v[48:51], s[10:11]
	s_add_u32 s94, s94, s80
	s_lshl_b32 s6, s94, 13
	s_add_u32 s10, s0, s6
	s_addc_u32 s11, s1, 0
	s_waitcnt vmcnt(33)
	global_store_dwordx4 v0, v[52:55], s[10:11]
	s_add_u32 s94, s94, s80
	s_lshl_b32 s6, s94, 13
	s_add_u32 s10, s0, s6
	s_addc_u32 s11, s1, 0
	s_waitcnt vmcnt(33)
	global_store_dwordx4 v0, v[56:59], s[10:11]
	s_add_u32 s94, s94, s80
	s_lshl_b32 s6, s94, 13
	s_add_u32 s10, s0, s6
	s_addc_u32 s11, s1, 0
	s_waitcnt vmcnt(33)
	global_store_dwordx4 v0, v[60:63], s[10:11]
	s_add_u32 s94, s94, s80
	s_lshl_b32 s6, s94, 13
	s_add_u32 s10, s0, s6
	s_addc_u32 s11, s1, 0
	s_waitcnt vmcnt(33)
	global_store_dwordx4 v0, v[64:67], s[10:11]
	s_add_u32 s94, s94, s80
	s_lshl_b32 s6, s94, 13
	s_add_u32 s10, s0, s6
	s_addc_u32 s11, s1, 0
	s_waitcnt vmcnt(33)
	global_store_dwordx4 v0, v[68:71], s[10:11]
	s_add_u32 s94, s94, s80
	s_lshl_b32 s6, s94, 13
	s_add_u32 s10, s0, s6
	s_addc_u32 s11, s1, 0
	s_waitcnt vmcnt(33)
	global_store_dwordx4 v0, v[72:75], s[10:11]
	s_add_u32 s94, s94, s80
	s_lshl_b32 s6, s94, 13
	s_add_u32 s10, s0, s6
	s_addc_u32 s11, s1, 0
	s_waitcnt vmcnt(33)
	global_store_dwordx4 v0, v[76:79], s[10:11]
	s_add_u32 s94, s94, s80
	s_lshl_b32 s6, s94, 13
	s_add_u32 s10, s0, s6
	s_addc_u32 s11, s1, 0
	s_waitcnt vmcnt(33)
	global_store_dwordx4 v0, v[80:83], s[10:11]
	s_add_u32 s94, s94, s80
	s_lshl_b32 s6, s94, 13
	s_add_u32 s10, s0, s6
	s_addc_u32 s11, s1, 0
	s_waitcnt vmcnt(33)
	global_store_dwordx4 v0, v[84:87], s[10:11]
	s_add_u32 s94, s94, s80
	s_lshl_b32 s6, s94, 13
	s_add_u32 s10, s0, s6
	s_addc_u32 s11, s1, 0
	s_waitcnt vmcnt(33)
	global_store_dwordx4 v0, v[88:91], s[10:11]
	s_add_u32 s94, s94, s80
	s_lshl_b32 s6, s94, 13
	s_add_u32 s10, s0, s6
	s_addc_u32 s11, s1, 0
	s_waitcnt vmcnt(33)
	global_store_dwordx4 v0, v[92:95], s[10:11]
	s_add_u32 s94, s94, s80
	s_lshl_b32 s6, s94, 13
	s_add_u32 s10, s0, s6
	s_addc_u32 s11, s1, 0
	s_waitcnt vmcnt(33)
	global_store_dwordx4 v0, v[96:99], s[10:11]
	s_add_u32 s94, s94, s80
	s_lshl_b32 s6, s94, 13
	s_add_u32 s10, s0, s6
	s_addc_u32 s11, s1, 0
	s_waitcnt vmcnt(33)
	global_store_dwordx4 v0, v[100:103], s[10:11]
	s_add_u32 s94, s94, s80
	s_lshl_b32 s6, s94, 13
	s_add_u32 s10, s0, s6
	s_addc_u32 s11, s1, 0
	s_waitcnt vmcnt(33)
	global_store_dwordx4 v0, v[104:107], s[10:11]
	s_add_u32 s94, s94, s80
	s_lshl_b32 s6, s94, 13
	s_add_u32 s10, s0, s6
	s_addc_u32 s11, s1, 0
	s_waitcnt vmcnt(33)
	global_store_dwordx4 v0, v[108:111], s[10:11]
	s_add_u32 s94, s94, s80
	s_lshl_b32 s6, s94, 13
	s_add_u32 s10, s0, s6
	s_addc_u32 s11, s1, 0
	s_waitcnt vmcnt(33)
	global_store_dwordx4 v0, v[112:115], s[10:11]
	s_add_u32 s94, s94, s80
	s_lshl_b32 s6, s94, 13
	s_add_u32 s10, s0, s6
	s_addc_u32 s11, s1, 0
	s_waitcnt vmcnt(33)
	global_store_dwordx4 v0, v[116:119], s[10:11]
	s_add_u32 s94, s94, s80
	s_lshl_b32 s6, s94, 13
	s_add_u32 s10, s0, s6
	s_addc_u32 s11, s1, 0
	s_waitcnt vmcnt(33)
	global_store_dwordx4 v0, v[120:123], s[10:11]
	s_add_u32 s94, s94, s80
	s_lshl_b32 s6, s94, 13
	s_add_u32 s10, s0, s6
	s_addc_u32 s11, s1, 0
	s_waitcnt vmcnt(33)
	global_store_dwordx4 v0, v[124:127], s[10:11]
	s_add_u32 s94, s94, s80
	s_lshl_b32 s6, s94, 13
	s_add_u32 s10, s0, s6
	s_addc_u32 s11, s1, 0
	s_waitcnt vmcnt(33)
	global_store_dwordx4 v0, v[128:131], s[10:11]
	s_add_u32 s94, s94, s80
	s_lshl_b32 s6, s94, 13
	s_add_u32 s10, s0, s6
	s_addc_u32 s11, s1, 0
	s_waitcnt vmcnt(33)
	global_store_dwordx4 v0, v[132:135], s[10:11]
	s_add_u32 s94, s94, s80
	s_lshl_b32 s6, s94, 13
	s_add_u32 s10, s0, s6
	s_addc_u32 s11, s1, 0
	s_waitcnt vmcnt(33)
	global_store_dwordx4 v0, v[136:139], s[10:11]
	s_add_u32 s94, s94, s80
	s_mov_b32 s90, s94
	s_branch .Lcp_batch_test
; __global__ void __launch_bounds__(512) mk_fwd(Params P) {
;     ...
;             for (size_t i = (size_t)bid * 512 + tid; i < (size_t)M * 256; i += (size_t)G * 512) {
;                 const int row = (int)(i >> 8), c = (int)(i & 255), bi = row / TB, rr = row - bi * TB;
;                 h4[i] = __builtin_nontemporal_load(rr < CTXL ? &c4[((size_t)bi * CTXL + rr) * 256 + c] : &x4[((size_t)bi * SEQ + (rr - CTXL)) * 256 + c]);
;             }
;             for (int e = bid * 512 + tid; e < 64 * 112; e += G * 512) {
.Lcp_tail:
	s_cmp_lt_u32 s90, 0x2200
	s_cbranch_scc0 .LBB0_569
	s_cmp_ge_u32 s90, 0x880
	s_cselect_b32 s6, 1, 0
	s_cmp_ge_u32 s90, 0x1100
	s_addc_u32 s6, s6, 0
	s_cmp_ge_u32 s90, 0x1980
	s_addc_u32 s6, s6, 0
	s_mul_i32 s7, s6, 0x880
	s_sub_u32 s7, s90, s7
	s_lshl_b32 s8, s7, 13
	s_cmp_lt_u32 s7, 0x80
	s_cselect_b32 s9, 20, 24
	s_cselect_b64 s[10:11], s[92:93], s[88:89]
	s_cselect_b32 s7, 0, 0x100000
	s_lshl_b32 s6, s6, s9
	s_add_u32 s6, s6, s8
	s_sub_u32 s6, s6, s7
	s_add_u32 s10, s10, s6
	s_addc_u32 s11, s11, 0
	global_load_dwordx4 v[4:7], v0, s[10:11] nt
	s_lshl_b32 s6, s90, 13
	s_add_u32 s10, s0, s6
	s_addc_u32 s11, s1, 0
	s_add_u32 s90, s90, s80
	s_waitcnt vmcnt(0)
	global_store_dwordx4 v0, v[4:7], s[10:11]
	s_branch .Lcp_tail
.LBB0_569:
	v_lshl_add_u32 v0, s2, 9, v146
	s_movk_i32 s3, 0x1c00
	v_cmp_gt_i32_e32 vcc, s3, v0
	s_and_saveexec_b64 s[6:7], vcc
	s_cbranch_execz .LBB0_586
	v_and_b32_e32 v8, 31, v146
	s_mov_b64 s[8:9], 0
	s_branch .LBB0_573
